# v16 + GEMM accumulators zeroed two registers at a time (v_pk_mov_b32)
# baseline (speedup 1.0000x reference)
.LBB0_393:
	s_ashr_i32 s19, s18, 31
	s_lshl_b64 s[0:1], s[18:19], 20
	s_add_u32 s20, s42, s0
	s_addc_u32 s21, s43, s1
	s_and_b64 s[0:1], s[4:5], exec
	s_cselect_b32 s7, s21, s25
	s_cselect_b32 s19, s20, s24
	s_ashr_i32 s17, s16, 31
	s_lshl_b64 s[0:1], s[16:17], 20
	s_add_u32 s22, s30, s0
	s_addc_u32 s23, s31, s1
	s_and_b64 s[0:1], s[4:5], exec
	s_cselect_b32 s17, s23, s27
	s_cselect_b32 s49, s22, s26
	s_add_u32 s24, s24, 0x80080
	s_addc_u32 s25, s25, 0
	s_add_u32 s58, s26, 0x100
	v_mov_b32_e32 v2, 0
	s_addc_u32 s59, s27, 0
	s_mov_b32 s60, -2
	v_mov_b32_e32 v3, v2
	s_waitcnt lgkmcnt(0)
	v_pk_mov_b32 v[4:5], v[2:3], v[2:3] op_sel:[0,1]
	v_pk_mov_b32 v[6:7], v[2:3], v[2:3] op_sel:[0,1]
	v_pk_mov_b32 v[8:9], v[2:3], v[2:3] op_sel:[0,1]
	v_pk_mov_b32 v[18:19], v[2:3], v[2:3] op_sel:[0,1]
	v_pk_mov_b32 v[20:21], v[2:3], v[2:3] op_sel:[0,1]
	v_pk_mov_b32 v[22:23], v[2:3], v[2:3] op_sel:[0,1]
	v_pk_mov_b32 v[24:25], v[2:3], v[2:3] op_sel:[0,1]
	s_waitcnt vmcnt(0)
	v_pk_mov_b32 v[34:35], v[2:3], v[2:3] op_sel:[0,1]
	v_pk_mov_b32 v[36:37], v[2:3], v[2:3] op_sel:[0,1]
	v_pk_mov_b32 v[38:39], v[2:3], v[2:3] op_sel:[0,1]
	v_pk_mov_b32 v[40:41], v[2:3], v[2:3] op_sel:[0,1]
	v_pk_mov_b32 v[50:51], v[2:3], v[2:3] op_sel:[0,1]
	v_pk_mov_b32 v[52:53], v[2:3], v[2:3] op_sel:[0,1]
	v_pk_mov_b32 v[54:55], v[2:3], v[2:3] op_sel:[0,1]
	v_pk_mov_b32 v[56:57], v[2:3], v[2:3] op_sel:[0,1]
	v_pk_mov_b32 v[10:11], v[2:3], v[2:3] op_sel:[0,1]
	v_pk_mov_b32 v[12:13], v[2:3], v[2:3] op_sel:[0,1]
	v_pk_mov_b32 v[14:15], v[2:3], v[2:3] op_sel:[0,1]
	v_pk_mov_b32 v[16:17], v[2:3], v[2:3] op_sel:[0,1]
	v_pk_mov_b32 v[26:27], v[2:3], v[2:3] op_sel:[0,1]
	v_pk_mov_b32 v[28:29], v[2:3], v[2:3] op_sel:[0,1]
	v_pk_mov_b32 v[30:31], v[2:3], v[2:3] op_sel:[0,1]
	v_pk_mov_b32 v[32:33], v[2:3], v[2:3] op_sel:[0,1]
	v_pk_mov_b32 v[42:43], v[2:3], v[2:3] op_sel:[0,1]
	v_pk_mov_b32 v[44:45], v[2:3], v[2:3] op_sel:[0,1]
	v_pk_mov_b32 v[46:47], v[2:3], v[2:3] op_sel:[0,1]
	v_pk_mov_b32 v[48:49], v[2:3], v[2:3] op_sel:[0,1]
	v_pk_mov_b32 v[58:59], v[2:3], v[2:3] op_sel:[0,1]
	v_pk_mov_b32 v[60:61], v[2:3], v[2:3] op_sel:[0,1]
	v_pk_mov_b32 v[62:63], v[2:3], v[2:3] op_sel:[0,1]
	v_pk_mov_b32 v[64:65], v[2:3], v[2:3] op_sel:[0,1]
	v_pk_mov_b32 v[66:67], v[2:3], v[2:3] op_sel:[0,1]
	v_pk_mov_b32 v[68:69], v[2:3], v[2:3] op_sel:[0,1]
	v_pk_mov_b32 v[70:71], v[2:3], v[2:3] op_sel:[0,1]
	v_pk_mov_b32 v[72:73], v[2:3], v[2:3] op_sel:[0,1]
	v_pk_mov_b32 v[82:83], v[2:3], v[2:3] op_sel:[0,1]
	v_pk_mov_b32 v[84:85], v[2:3], v[2:3] op_sel:[0,1]
	v_pk_mov_b32 v[86:87], v[2:3], v[2:3] op_sel:[0,1]
	v_pk_mov_b32 v[88:89], v[2:3], v[2:3] op_sel:[0,1]
	v_pk_mov_b32 v[98:99], v[2:3], v[2:3] op_sel:[0,1]
	v_pk_mov_b32 v[100:101], v[2:3], v[2:3] op_sel:[0,1]
	v_pk_mov_b32 v[102:103], v[2:3], v[2:3] op_sel:[0,1]
	v_pk_mov_b32 v[104:105], v[2:3], v[2:3] op_sel:[0,1]
	v_pk_mov_b32 v[114:115], v[2:3], v[2:3] op_sel:[0,1]
	v_pk_mov_b32 v[116:117], v[2:3], v[2:3] op_sel:[0,1]
	v_pk_mov_b32 v[118:119], v[2:3], v[2:3] op_sel:[0,1]
	v_pk_mov_b32 v[120:121], v[2:3], v[2:3] op_sel:[0,1]
	v_pk_mov_b32 v[74:75], v[2:3], v[2:3] op_sel:[0,1]
	v_pk_mov_b32 v[76:77], v[2:3], v[2:3] op_sel:[0,1]
	v_pk_mov_b32 v[78:79], v[2:3], v[2:3] op_sel:[0,1]
	v_pk_mov_b32 v[80:81], v[2:3], v[2:3] op_sel:[0,1]
	v_pk_mov_b32 v[90:91], v[2:3], v[2:3] op_sel:[0,1]
	v_pk_mov_b32 v[92:93], v[2:3], v[2:3] op_sel:[0,1]
	v_pk_mov_b32 v[94:95], v[2:3], v[2:3] op_sel:[0,1]
	v_pk_mov_b32 v[96:97], v[2:3], v[2:3] op_sel:[0,1]
	v_pk_mov_b32 v[106:107], v[2:3], v[2:3] op_sel:[0,1]
	v_pk_mov_b32 v[108:109], v[2:3], v[2:3] op_sel:[0,1]
	v_pk_mov_b32 v[110:111], v[2:3], v[2:3] op_sel:[0,1]
	v_pk_mov_b32 v[112:113], v[2:3], v[2:3] op_sel:[0,1]
	v_pk_mov_b32 v[122:123], v[2:3], v[2:3] op_sel:[0,1]
	v_pk_mov_b32 v[124:125], v[2:3], v[2:3] op_sel:[0,1]
	v_pk_mov_b32 v[126:127], v[2:3], v[2:3] op_sel:[0,1]
	v_pk_mov_b32 v[128:129], v[2:3], v[2:3] op_sel:[0,1]

.LBB0_691:
	s_ashr_i32 s11, s10, 31
	s_lshl_b64 s[0:1], s[10:11], 21
	s_add_u32 s14, s78, s0
	s_addc_u32 s15, s79, s1
	s_and_b64 s[0:1], s[2:3], exec
	s_cselect_b32 s11, s15, s19
	s_cselect_b32 s49, s14, s18
	s_ashr_i32 s9, s8, 31
	s_lshl_b64 s[0:1], s[8:9], 21
	s_add_u32 s16, s24, s0
	s_addc_u32 s17, s25, s1
	s_and_b64 s[0:1], s[2:3], exec
	s_cselect_b32 s9, s17, s21
	s_cselect_b32 s58, s16, s20
	s_add_u32 s18, s18, 0x100080
	s_addc_u32 s19, s19, 0
	s_add_u32 s59, s20, 0x100
	v_mov_b32_e32 v2, 0
	s_addc_u32 s60, s21, 0
	s_mov_b32 s61, -2
	v_mov_b32_e32 v3, v2
	v_pk_mov_b32 v[4:5], v[2:3], v[2:3] op_sel:[0,1]
	v_pk_mov_b32 v[6:7], v[2:3], v[2:3] op_sel:[0,1]
	v_pk_mov_b32 v[8:9], v[2:3], v[2:3] op_sel:[0,1]
	v_pk_mov_b32 v[18:19], v[2:3], v[2:3] op_sel:[0,1]
	v_pk_mov_b32 v[20:21], v[2:3], v[2:3] op_sel:[0,1]
	v_pk_mov_b32 v[22:23], v[2:3], v[2:3] op_sel:[0,1]
	v_pk_mov_b32 v[24:25], v[2:3], v[2:3] op_sel:[0,1]
	v_pk_mov_b32 v[34:35], v[2:3], v[2:3] op_sel:[0,1]
	v_pk_mov_b32 v[36:37], v[2:3], v[2:3] op_sel:[0,1]
	v_pk_mov_b32 v[38:39], v[2:3], v[2:3] op_sel:[0,1]
	v_pk_mov_b32 v[40:41], v[2:3], v[2:3] op_sel:[0,1]
	v_pk_mov_b32 v[50:51], v[2:3], v[2:3] op_sel:[0,1]
	v_pk_mov_b32 v[52:53], v[2:3], v[2:3] op_sel:[0,1]
	v_pk_mov_b32 v[54:55], v[2:3], v[2:3] op_sel:[0,1]
	v_pk_mov_b32 v[56:57], v[2:3], v[2:3] op_sel:[0,1]
	v_pk_mov_b32 v[10:11], v[2:3], v[2:3] op_sel:[0,1]
	v_pk_mov_b32 v[12:13], v[2:3], v[2:3] op_sel:[0,1]
	v_pk_mov_b32 v[14:15], v[2:3], v[2:3] op_sel:[0,1]
	v_pk_mov_b32 v[16:17], v[2:3], v[2:3] op_sel:[0,1]
	v_pk_mov_b32 v[26:27], v[2:3], v[2:3] op_sel:[0,1]
	v_pk_mov_b32 v[28:29], v[2:3], v[2:3] op_sel:[0,1]
	v_pk_mov_b32 v[30:31], v[2:3], v[2:3] op_sel:[0,1]
	v_pk_mov_b32 v[32:33], v[2:3], v[2:3] op_sel:[0,1]
	v_pk_mov_b32 v[42:43], v[2:3], v[2:3] op_sel:[0,1]
	v_pk_mov_b32 v[44:45], v[2:3], v[2:3] op_sel:[0,1]
	v_pk_mov_b32 v[46:47], v[2:3], v[2:3] op_sel:[0,1]
	v_pk_mov_b32 v[48:49], v[2:3], v[2:3] op_sel:[0,1]
	v_pk_mov_b32 v[58:59], v[2:3], v[2:3] op_sel:[0,1]
	v_pk_mov_b32 v[60:61], v[2:3], v[2:3] op_sel:[0,1]
	v_pk_mov_b32 v[62:63], v[2:3], v[2:3] op_sel:[0,1]
	v_pk_mov_b32 v[64:65], v[2:3], v[2:3] op_sel:[0,1]
	v_pk_mov_b32 v[66:67], v[2:3], v[2:3] op_sel:[0,1]
	v_pk_mov_b32 v[68:69], v[2:3], v[2:3] op_sel:[0,1]
	v_pk_mov_b32 v[70:71], v[2:3], v[2:3] op_sel:[0,1]
	v_pk_mov_b32 v[72:73], v[2:3], v[2:3] op_sel:[0,1]
	v_pk_mov_b32 v[90:91], v[2:3], v[2:3] op_sel:[0,1]
	v_pk_mov_b32 v[92:93], v[2:3], v[2:3] op_sel:[0,1]
	v_pk_mov_b32 v[102:103], v[2:3], v[2:3] op_sel:[0,1]
	v_pk_mov_b32 v[104:105], v[2:3], v[2:3] op_sel:[0,1]
	v_pk_mov_b32 v[122:123], v[2:3], v[2:3] op_sel:[0,1]
	v_pk_mov_b32 v[124:125], v[2:3], v[2:3] op_sel:[0,1]
	v_pk_mov_b32 v[130:131], v[2:3], v[2:3] op_sel:[0,1]
	v_pk_mov_b32 v[132:133], v[2:3], v[2:3] op_sel:[0,1]
	v_pk_mov_b32 v[150:151], v[2:3], v[2:3] op_sel:[0,1]
	v_pk_mov_b32 v[152:153], v[2:3], v[2:3] op_sel:[0,1]
	v_pk_mov_b32 v[154:155], v[2:3], v[2:3] op_sel:[0,1]
	v_pk_mov_b32 v[156:157], v[2:3], v[2:3] op_sel:[0,1]
	v_pk_mov_b32 v[74:75], v[2:3], v[2:3] op_sel:[0,1]
	v_pk_mov_b32 v[76:77], v[2:3], v[2:3] op_sel:[0,1]
	v_pk_mov_b32 v[82:83], v[2:3], v[2:3] op_sel:[0,1]
	v_pk_mov_b32 v[84:85], v[2:3], v[2:3] op_sel:[0,1]
	v_pk_mov_b32 v[114:115], v[2:3], v[2:3] op_sel:[0,1]
	v_pk_mov_b32 v[116:117], v[2:3], v[2:3] op_sel:[0,1]
	v_pk_mov_b32 v[118:119], v[2:3], v[2:3] op_sel:[0,1]
	v_pk_mov_b32 v[120:121], v[2:3], v[2:3] op_sel:[0,1]
	v_pk_mov_b32 v[138:139], v[2:3], v[2:3] op_sel:[0,1]
	v_pk_mov_b32 v[140:141], v[2:3], v[2:3] op_sel:[0,1]
	v_pk_mov_b32 v[142:143], v[2:3], v[2:3] op_sel:[0,1]
	v_pk_mov_b32 v[144:145], v[2:3], v[2:3] op_sel:[0,1]
	v_pk_mov_b32 v[162:163], v[2:3], v[2:3] op_sel:[0,1]
	v_pk_mov_b32 v[164:165], v[2:3], v[2:3] op_sel:[0,1]
	v_pk_mov_b32 v[170:171], v[2:3], v[2:3] op_sel:[0,1]
	v_pk_mov_b32 v[172:173], v[2:3], v[2:3] op_sel:[0,1]

.LBB0_711:
	s_add_u32 s18, s18, 0x100080
	s_addc_u32 s19, s19, 0
	s_add_u32 s9, s20, 0x100
	v_mov_b32_e32 v2, 0
	s_addc_u32 s11, s21, 0
	s_mov_b32 s49, -2
	v_mov_b32_e32 v3, v2
	v_pk_mov_b32 v[4:5], v[2:3], v[2:3] op_sel:[0,1]
	v_pk_mov_b32 v[6:7], v[2:3], v[2:3] op_sel:[0,1]
	v_pk_mov_b32 v[8:9], v[2:3], v[2:3] op_sel:[0,1]
	v_pk_mov_b32 v[10:11], v[2:3], v[2:3] op_sel:[0,1]
	v_pk_mov_b32 v[12:13], v[2:3], v[2:3] op_sel:[0,1]
	v_pk_mov_b32 v[14:15], v[2:3], v[2:3] op_sel:[0,1]
	v_pk_mov_b32 v[16:17], v[2:3], v[2:3] op_sel:[0,1]
	v_pk_mov_b32 v[26:27], v[2:3], v[2:3] op_sel:[0,1]
	v_pk_mov_b32 v[28:29], v[2:3], v[2:3] op_sel:[0,1]
	v_pk_mov_b32 v[30:31], v[2:3], v[2:3] op_sel:[0,1]
	v_pk_mov_b32 v[32:33], v[2:3], v[2:3] op_sel:[0,1]
	v_pk_mov_b32 v[42:43], v[2:3], v[2:3] op_sel:[0,1]
	v_pk_mov_b32 v[44:45], v[2:3], v[2:3] op_sel:[0,1]
	v_pk_mov_b32 v[46:47], v[2:3], v[2:3] op_sel:[0,1]
	v_pk_mov_b32 v[48:49], v[2:3], v[2:3] op_sel:[0,1]
	v_pk_mov_b32 v[18:19], v[2:3], v[2:3] op_sel:[0,1]
	v_pk_mov_b32 v[20:21], v[2:3], v[2:3] op_sel:[0,1]
	v_pk_mov_b32 v[22:23], v[2:3], v[2:3] op_sel:[0,1]
	v_pk_mov_b32 v[24:25], v[2:3], v[2:3] op_sel:[0,1]
	v_pk_mov_b32 v[34:35], v[2:3], v[2:3] op_sel:[0,1]
	v_pk_mov_b32 v[36:37], v[2:3], v[2:3] op_sel:[0,1]
	v_pk_mov_b32 v[38:39], v[2:3], v[2:3] op_sel:[0,1]
	v_pk_mov_b32 v[40:41], v[2:3], v[2:3] op_sel:[0,1]
	v_pk_mov_b32 v[50:51], v[2:3], v[2:3] op_sel:[0,1]
	v_pk_mov_b32 v[52:53], v[2:3], v[2:3] op_sel:[0,1]
	v_pk_mov_b32 v[54:55], v[2:3], v[2:3] op_sel:[0,1]
	v_pk_mov_b32 v[56:57], v[2:3], v[2:3] op_sel:[0,1]
	v_pk_mov_b32 v[58:59], v[2:3], v[2:3] op_sel:[0,1]
	v_pk_mov_b32 v[60:61], v[2:3], v[2:3] op_sel:[0,1]
	v_pk_mov_b32 v[62:63], v[2:3], v[2:3] op_sel:[0,1]
	v_pk_mov_b32 v[64:65], v[2:3], v[2:3] op_sel:[0,1]
	v_pk_mov_b32 v[66:67], v[2:3], v[2:3] op_sel:[0,1]
	v_pk_mov_b32 v[68:69], v[2:3], v[2:3] op_sel:[0,1]
	v_pk_mov_b32 v[70:71], v[2:3], v[2:3] op_sel:[0,1]
	v_pk_mov_b32 v[72:73], v[2:3], v[2:3] op_sel:[0,1]
	v_pk_mov_b32 v[74:75], v[2:3], v[2:3] op_sel:[0,1]
	v_pk_mov_b32 v[76:77], v[2:3], v[2:3] op_sel:[0,1]
	v_pk_mov_b32 v[78:79], v[2:3], v[2:3] op_sel:[0,1]
	v_pk_mov_b32 v[80:81], v[2:3], v[2:3] op_sel:[0,1]
	v_pk_mov_b32 v[86:87], v[2:3], v[2:3] op_sel:[0,1]
	v_pk_mov_b32 v[88:89], v[2:3], v[2:3] op_sel:[0,1]
	v_pk_mov_b32 v[94:95], v[2:3], v[2:3] op_sel:[0,1]
	v_pk_mov_b32 v[96:97], v[2:3], v[2:3] op_sel:[0,1]
	v_pk_mov_b32 v[102:103], v[2:3], v[2:3] op_sel:[0,1]
	v_pk_mov_b32 v[104:105], v[2:3], v[2:3] op_sel:[0,1]
	v_pk_mov_b32 v[110:111], v[2:3], v[2:3] op_sel:[0,1]
	v_pk_mov_b32 v[112:113], v[2:3], v[2:3] op_sel:[0,1]
	v_pk_mov_b32 v[82:83], v[2:3], v[2:3] op_sel:[0,1]
	v_pk_mov_b32 v[84:85], v[2:3], v[2:3] op_sel:[0,1]
	v_pk_mov_b32 v[90:91], v[2:3], v[2:3] op_sel:[0,1]
	v_pk_mov_b32 v[92:93], v[2:3], v[2:3] op_sel:[0,1]
	v_pk_mov_b32 v[98:99], v[2:3], v[2:3] op_sel:[0,1]
	v_pk_mov_b32 v[100:101], v[2:3], v[2:3] op_sel:[0,1]
	v_pk_mov_b32 v[106:107], v[2:3], v[2:3] op_sel:[0,1]
	v_pk_mov_b32 v[108:109], v[2:3], v[2:3] op_sel:[0,1]
	v_pk_mov_b32 v[114:115], v[2:3], v[2:3] op_sel:[0,1]
	v_pk_mov_b32 v[116:117], v[2:3], v[2:3] op_sel:[0,1]
	v_pk_mov_b32 v[118:119], v[2:3], v[2:3] op_sel:[0,1]
	v_pk_mov_b32 v[120:121], v[2:3], v[2:3] op_sel:[0,1]
	v_pk_mov_b32 v[122:123], v[2:3], v[2:3] op_sel:[0,1]
	v_pk_mov_b32 v[124:125], v[2:3], v[2:3] op_sel:[0,1]
	v_pk_mov_b32 v[126:127], v[2:3], v[2:3] op_sel:[0,1]
	v_pk_mov_b32 v[128:129], v[2:3], v[2:3] op_sel:[0,1]

.LBB0_836:
	s_ashr_i32 s11, s10, 31
	s_lshl_b64 s[0:1], s[10:11], 20
	s_add_u32 s14, s42, s0
	s_addc_u32 s15, s43, s1
	s_and_b64 s[0:1], s[2:3], exec
	s_cselect_b32 s11, s15, s19
	s_cselect_b32 s38, s14, s18
	s_ashr_i32 s9, s8, 31
	s_lshl_b64 s[0:1], s[8:9], 20
	s_add_u32 s16, s24, s0
	s_addc_u32 s17, s25, s1
	s_and_b64 s[0:1], s[2:3], exec
	s_cselect_b32 s9, s17, s21
	s_cselect_b32 s39, s16, s20
	s_add_u32 s18, s18, 0x80080
	s_addc_u32 s19, s19, 0
	s_add_u32 s49, s20, 0x100
	v_mov_b32_e32 v2, 0
	s_addc_u32 s58, s21, 0
	s_mov_b32 s59, -2
	v_mov_b32_e32 v3, v2
	v_pk_mov_b32 v[4:5], v[2:3], v[2:3] op_sel:[0,1]
	v_pk_mov_b32 v[10:11], v[2:3], v[2:3] op_sel:[0,1]
	v_pk_mov_b32 v[12:13], v[2:3], v[2:3] op_sel:[0,1]
	v_pk_mov_b32 v[18:19], v[2:3], v[2:3] op_sel:[0,1]
	v_pk_mov_b32 v[20:21], v[2:3], v[2:3] op_sel:[0,1]
	v_pk_mov_b32 v[26:27], v[2:3], v[2:3] op_sel:[0,1]
	v_pk_mov_b32 v[28:29], v[2:3], v[2:3] op_sel:[0,1]
	v_pk_mov_b32 v[34:35], v[2:3], v[2:3] op_sel:[0,1]
	v_pk_mov_b32 v[36:37], v[2:3], v[2:3] op_sel:[0,1]
	v_pk_mov_b32 v[42:43], v[2:3], v[2:3] op_sel:[0,1]
	v_pk_mov_b32 v[44:45], v[2:3], v[2:3] op_sel:[0,1]
	v_pk_mov_b32 v[50:51], v[2:3], v[2:3] op_sel:[0,1]
	v_pk_mov_b32 v[52:53], v[2:3], v[2:3] op_sel:[0,1]
	v_pk_mov_b32 v[58:59], v[2:3], v[2:3] op_sel:[0,1]
	v_pk_mov_b32 v[60:61], v[2:3], v[2:3] op_sel:[0,1]
	v_pk_mov_b32 v[6:7], v[2:3], v[2:3] op_sel:[0,1]
	v_pk_mov_b32 v[8:9], v[2:3], v[2:3] op_sel:[0,1]
	v_pk_mov_b32 v[14:15], v[2:3], v[2:3] op_sel:[0,1]
	v_pk_mov_b32 v[16:17], v[2:3], v[2:3] op_sel:[0,1]
	v_pk_mov_b32 v[22:23], v[2:3], v[2:3] op_sel:[0,1]
	v_pk_mov_b32 v[24:25], v[2:3], v[2:3] op_sel:[0,1]
	v_pk_mov_b32 v[30:31], v[2:3], v[2:3] op_sel:[0,1]
	v_pk_mov_b32 v[32:33], v[2:3], v[2:3] op_sel:[0,1]
	v_pk_mov_b32 v[38:39], v[2:3], v[2:3] op_sel:[0,1]
	v_pk_mov_b32 v[40:41], v[2:3], v[2:3] op_sel:[0,1]
	v_pk_mov_b32 v[46:47], v[2:3], v[2:3] op_sel:[0,1]
	v_pk_mov_b32 v[48:49], v[2:3], v[2:3] op_sel:[0,1]
	v_pk_mov_b32 v[54:55], v[2:3], v[2:3] op_sel:[0,1]
	v_pk_mov_b32 v[56:57], v[2:3], v[2:3] op_sel:[0,1]
	v_pk_mov_b32 v[62:63], v[2:3], v[2:3] op_sel:[0,1]
	v_pk_mov_b32 v[64:65], v[2:3], v[2:3] op_sel:[0,1]
	v_pk_mov_b32 v[66:67], v[2:3], v[2:3] op_sel:[0,1]
	v_pk_mov_b32 v[68:69], v[2:3], v[2:3] op_sel:[0,1]
	v_pk_mov_b32 v[74:75], v[2:3], v[2:3] op_sel:[0,1]
	v_pk_mov_b32 v[76:77], v[2:3], v[2:3] op_sel:[0,1]
	v_pk_mov_b32 v[82:83], v[2:3], v[2:3] op_sel:[0,1]
	v_pk_mov_b32 v[84:85], v[2:3], v[2:3] op_sel:[0,1]
	v_pk_mov_b32 v[90:91], v[2:3], v[2:3] op_sel:[0,1]
	v_pk_mov_b32 v[92:93], v[2:3], v[2:3] op_sel:[0,1]
	v_pk_mov_b32 v[98:99], v[2:3], v[2:3] op_sel:[0,1]
	v_pk_mov_b32 v[100:101], v[2:3], v[2:3] op_sel:[0,1]
	v_pk_mov_b32 v[106:107], v[2:3], v[2:3] op_sel:[0,1]
	v_pk_mov_b32 v[108:109], v[2:3], v[2:3] op_sel:[0,1]
	v_pk_mov_b32 v[114:115], v[2:3], v[2:3] op_sel:[0,1]
	v_pk_mov_b32 v[116:117], v[2:3], v[2:3] op_sel:[0,1]
	v_pk_mov_b32 v[122:123], v[2:3], v[2:3] op_sel:[0,1]
	v_pk_mov_b32 v[124:125], v[2:3], v[2:3] op_sel:[0,1]
	v_pk_mov_b32 v[70:71], v[2:3], v[2:3] op_sel:[0,1]
	v_pk_mov_b32 v[72:73], v[2:3], v[2:3] op_sel:[0,1]
	v_pk_mov_b32 v[78:79], v[2:3], v[2:3] op_sel:[0,1]
	v_pk_mov_b32 v[80:81], v[2:3], v[2:3] op_sel:[0,1]
	v_pk_mov_b32 v[86:87], v[2:3], v[2:3] op_sel:[0,1]
	v_pk_mov_b32 v[88:89], v[2:3], v[2:3] op_sel:[0,1]
	v_pk_mov_b32 v[94:95], v[2:3], v[2:3] op_sel:[0,1]
	v_pk_mov_b32 v[96:97], v[2:3], v[2:3] op_sel:[0,1]
	v_pk_mov_b32 v[102:103], v[2:3], v[2:3] op_sel:[0,1]
	v_pk_mov_b32 v[104:105], v[2:3], v[2:3] op_sel:[0,1]
	v_pk_mov_b32 v[110:111], v[2:3], v[2:3] op_sel:[0,1]
	v_pk_mov_b32 v[112:113], v[2:3], v[2:3] op_sel:[0,1]
	v_pk_mov_b32 v[118:119], v[2:3], v[2:3] op_sel:[0,1]
	v_pk_mov_b32 v[120:121], v[2:3], v[2:3] op_sel:[0,1]
	v_pk_mov_b32 v[126:127], v[2:3], v[2:3] op_sel:[0,1]
	v_pk_mov_b32 v[128:129], v[2:3], v[2:3] op_sel:[0,1]

.LBB0_969:
	s_add_u32 s49, s16, 0x100
	v_mov_b32_e32 v2, 0
	s_addc_u32 s58, s17, 0
	s_mov_b32 s59, -2
	v_mov_b32_e32 v3, v2
	v_pk_mov_b32 v[4:5], v[2:3], v[2:3] op_sel:[0,1]
	v_pk_mov_b32 v[6:7], v[2:3], v[2:3] op_sel:[0,1]
	v_pk_mov_b32 v[8:9], v[2:3], v[2:3] op_sel:[0,1]
	v_pk_mov_b32 v[18:19], v[2:3], v[2:3] op_sel:[0,1]
	v_pk_mov_b32 v[20:21], v[2:3], v[2:3] op_sel:[0,1]
	v_pk_mov_b32 v[22:23], v[2:3], v[2:3] op_sel:[0,1]
	v_pk_mov_b32 v[24:25], v[2:3], v[2:3] op_sel:[0,1]
	v_pk_mov_b32 v[34:35], v[2:3], v[2:3] op_sel:[0,1]
	v_pk_mov_b32 v[36:37], v[2:3], v[2:3] op_sel:[0,1]
	v_pk_mov_b32 v[38:39], v[2:3], v[2:3] op_sel:[0,1]
	v_pk_mov_b32 v[40:41], v[2:3], v[2:3] op_sel:[0,1]
	v_pk_mov_b32 v[50:51], v[2:3], v[2:3] op_sel:[0,1]
	v_pk_mov_b32 v[52:53], v[2:3], v[2:3] op_sel:[0,1]
	v_pk_mov_b32 v[54:55], v[2:3], v[2:3] op_sel:[0,1]
	v_pk_mov_b32 v[56:57], v[2:3], v[2:3] op_sel:[0,1]
	v_pk_mov_b32 v[10:11], v[2:3], v[2:3] op_sel:[0,1]
	v_pk_mov_b32 v[12:13], v[2:3], v[2:3] op_sel:[0,1]
	v_pk_mov_b32 v[14:15], v[2:3], v[2:3] op_sel:[0,1]
	v_pk_mov_b32 v[16:17], v[2:3], v[2:3] op_sel:[0,1]
	v_pk_mov_b32 v[26:27], v[2:3], v[2:3] op_sel:[0,1]
	v_pk_mov_b32 v[28:29], v[2:3], v[2:3] op_sel:[0,1]
	v_pk_mov_b32 v[30:31], v[2:3], v[2:3] op_sel:[0,1]
	v_pk_mov_b32 v[32:33], v[2:3], v[2:3] op_sel:[0,1]
	v_pk_mov_b32 v[42:43], v[2:3], v[2:3] op_sel:[0,1]
	v_pk_mov_b32 v[44:45], v[2:3], v[2:3] op_sel:[0,1]
	v_pk_mov_b32 v[46:47], v[2:3], v[2:3] op_sel:[0,1]
	v_pk_mov_b32 v[48:49], v[2:3], v[2:3] op_sel:[0,1]
	v_pk_mov_b32 v[58:59], v[2:3], v[2:3] op_sel:[0,1]
	v_pk_mov_b32 v[60:61], v[2:3], v[2:3] op_sel:[0,1]
	v_pk_mov_b32 v[62:63], v[2:3], v[2:3] op_sel:[0,1]
	v_pk_mov_b32 v[64:65], v[2:3], v[2:3] op_sel:[0,1]
	v_pk_mov_b32 v[66:67], v[2:3], v[2:3] op_sel:[0,1]
	v_pk_mov_b32 v[68:69], v[2:3], v[2:3] op_sel:[0,1]
	v_pk_mov_b32 v[70:71], v[2:3], v[2:3] op_sel:[0,1]
	v_pk_mov_b32 v[72:73], v[2:3], v[2:3] op_sel:[0,1]
	v_pk_mov_b32 v[90:91], v[2:3], v[2:3] op_sel:[0,1]
	v_pk_mov_b32 v[92:93], v[2:3], v[2:3] op_sel:[0,1]
	v_pk_mov_b32 v[102:103], v[2:3], v[2:3] op_sel:[0,1]
	v_pk_mov_b32 v[104:105], v[2:3], v[2:3] op_sel:[0,1]
	v_pk_mov_b32 v[122:123], v[2:3], v[2:3] op_sel:[0,1]
	v_pk_mov_b32 v[124:125], v[2:3], v[2:3] op_sel:[0,1]
	v_pk_mov_b32 v[130:131], v[2:3], v[2:3] op_sel:[0,1]
	v_pk_mov_b32 v[132:133], v[2:3], v[2:3] op_sel:[0,1]
	v_pk_mov_b32 v[150:151], v[2:3], v[2:3] op_sel:[0,1]
	v_pk_mov_b32 v[152:153], v[2:3], v[2:3] op_sel:[0,1]
	v_pk_mov_b32 v[154:155], v[2:3], v[2:3] op_sel:[0,1]
	v_pk_mov_b32 v[156:157], v[2:3], v[2:3] op_sel:[0,1]
	v_pk_mov_b32 v[74:75], v[2:3], v[2:3] op_sel:[0,1]
	v_pk_mov_b32 v[76:77], v[2:3], v[2:3] op_sel:[0,1]
	v_pk_mov_b32 v[86:87], v[2:3], v[2:3] op_sel:[0,1]
	v_pk_mov_b32 v[88:89], v[2:3], v[2:3] op_sel:[0,1]
	v_pk_mov_b32 v[114:115], v[2:3], v[2:3] op_sel:[0,1]
	v_pk_mov_b32 v[116:117], v[2:3], v[2:3] op_sel:[0,1]
	v_pk_mov_b32 v[118:119], v[2:3], v[2:3] op_sel:[0,1]
	v_pk_mov_b32 v[120:121], v[2:3], v[2:3] op_sel:[0,1]
	v_pk_mov_b32 v[138:139], v[2:3], v[2:3] op_sel:[0,1]
	v_pk_mov_b32 v[140:141], v[2:3], v[2:3] op_sel:[0,1]
	v_pk_mov_b32 v[142:143], v[2:3], v[2:3] op_sel:[0,1]
	v_pk_mov_b32 v[144:145], v[2:3], v[2:3] op_sel:[0,1]
	v_pk_mov_b32 v[162:163], v[2:3], v[2:3] op_sel:[0,1]
	v_pk_mov_b32 v[164:165], v[2:3], v[2:3] op_sel:[0,1]
	v_pk_mov_b32 v[170:171], v[2:3], v[2:3] op_sel:[0,1]
	v_pk_mov_b32 v[172:173], v[2:3], v[2:3] op_sel:[0,1]

.LBB0_989:
	s_add_u32 s49, s4, 0x100
	v_mov_b32_e32 v2, 0
	s_addc_u32 s58, s5, 0
	s_mov_b32 s59, -2
	v_mov_b32_e32 v3, v2
	v_pk_mov_b32 v[4:5], v[2:3], v[2:3] op_sel:[0,1]
	v_pk_mov_b32 v[6:7], v[2:3], v[2:3] op_sel:[0,1]
	v_pk_mov_b32 v[8:9], v[2:3], v[2:3] op_sel:[0,1]
	v_pk_mov_b32 v[10:11], v[2:3], v[2:3] op_sel:[0,1]
	v_pk_mov_b32 v[12:13], v[2:3], v[2:3] op_sel:[0,1]
	v_pk_mov_b32 v[14:15], v[2:3], v[2:3] op_sel:[0,1]
	v_pk_mov_b32 v[16:17], v[2:3], v[2:3] op_sel:[0,1]
	v_pk_mov_b32 v[26:27], v[2:3], v[2:3] op_sel:[0,1]
	v_pk_mov_b32 v[28:29], v[2:3], v[2:3] op_sel:[0,1]
	v_pk_mov_b32 v[30:31], v[2:3], v[2:3] op_sel:[0,1]
	v_pk_mov_b32 v[32:33], v[2:3], v[2:3] op_sel:[0,1]
	v_pk_mov_b32 v[42:43], v[2:3], v[2:3] op_sel:[0,1]
	v_pk_mov_b32 v[44:45], v[2:3], v[2:3] op_sel:[0,1]
	v_pk_mov_b32 v[46:47], v[2:3], v[2:3] op_sel:[0,1]
	v_pk_mov_b32 v[48:49], v[2:3], v[2:3] op_sel:[0,1]
	v_pk_mov_b32 v[18:19], v[2:3], v[2:3] op_sel:[0,1]
	v_pk_mov_b32 v[20:21], v[2:3], v[2:3] op_sel:[0,1]
	v_pk_mov_b32 v[22:23], v[2:3], v[2:3] op_sel:[0,1]
	v_pk_mov_b32 v[24:25], v[2:3], v[2:3] op_sel:[0,1]
	v_pk_mov_b32 v[34:35], v[2:3], v[2:3] op_sel:[0,1]
	v_pk_mov_b32 v[36:37], v[2:3], v[2:3] op_sel:[0,1]
	v_pk_mov_b32 v[38:39], v[2:3], v[2:3] op_sel:[0,1]
	v_pk_mov_b32 v[40:41], v[2:3], v[2:3] op_sel:[0,1]
	v_pk_mov_b32 v[50:51], v[2:3], v[2:3] op_sel:[0,1]
	v_pk_mov_b32 v[52:53], v[2:3], v[2:3] op_sel:[0,1]
	v_pk_mov_b32 v[54:55], v[2:3], v[2:3] op_sel:[0,1]
	v_pk_mov_b32 v[56:57], v[2:3], v[2:3] op_sel:[0,1]
	v_pk_mov_b32 v[58:59], v[2:3], v[2:3] op_sel:[0,1]
	v_pk_mov_b32 v[60:61], v[2:3], v[2:3] op_sel:[0,1]
	v_pk_mov_b32 v[62:63], v[2:3], v[2:3] op_sel:[0,1]
	v_pk_mov_b32 v[64:65], v[2:3], v[2:3] op_sel:[0,1]
	v_pk_mov_b32 v[66:67], v[2:3], v[2:3] op_sel:[0,1]
	v_pk_mov_b32 v[68:69], v[2:3], v[2:3] op_sel:[0,1]
	v_pk_mov_b32 v[70:71], v[2:3], v[2:3] op_sel:[0,1]
	v_pk_mov_b32 v[72:73], v[2:3], v[2:3] op_sel:[0,1]
	v_pk_mov_b32 v[74:75], v[2:3], v[2:3] op_sel:[0,1]
	v_pk_mov_b32 v[76:77], v[2:3], v[2:3] op_sel:[0,1]
	v_pk_mov_b32 v[78:79], v[2:3], v[2:3] op_sel:[0,1]
	v_pk_mov_b32 v[80:81], v[2:3], v[2:3] op_sel:[0,1]
	v_pk_mov_b32 v[86:87], v[2:3], v[2:3] op_sel:[0,1]
	v_pk_mov_b32 v[88:89], v[2:3], v[2:3] op_sel:[0,1]
	v_pk_mov_b32 v[94:95], v[2:3], v[2:3] op_sel:[0,1]
	v_pk_mov_b32 v[96:97], v[2:3], v[2:3] op_sel:[0,1]
	v_pk_mov_b32 v[102:103], v[2:3], v[2:3] op_sel:[0,1]
	v_pk_mov_b32 v[104:105], v[2:3], v[2:3] op_sel:[0,1]
	v_pk_mov_b32 v[110:111], v[2:3], v[2:3] op_sel:[0,1]
	v_pk_mov_b32 v[112:113], v[2:3], v[2:3] op_sel:[0,1]
	v_pk_mov_b32 v[82:83], v[2:3], v[2:3] op_sel:[0,1]
	v_pk_mov_b32 v[84:85], v[2:3], v[2:3] op_sel:[0,1]
	v_pk_mov_b32 v[90:91], v[2:3], v[2:3] op_sel:[0,1]
	v_pk_mov_b32 v[92:93], v[2:3], v[2:3] op_sel:[0,1]
	v_pk_mov_b32 v[98:99], v[2:3], v[2:3] op_sel:[0,1]
	v_pk_mov_b32 v[100:101], v[2:3], v[2:3] op_sel:[0,1]
	v_pk_mov_b32 v[106:107], v[2:3], v[2:3] op_sel:[0,1]
	v_pk_mov_b32 v[108:109], v[2:3], v[2:3] op_sel:[0,1]
	v_pk_mov_b32 v[114:115], v[2:3], v[2:3] op_sel:[0,1]
	v_pk_mov_b32 v[116:117], v[2:3], v[2:3] op_sel:[0,1]
	v_pk_mov_b32 v[118:119], v[2:3], v[2:3] op_sel:[0,1]
	v_pk_mov_b32 v[120:121], v[2:3], v[2:3] op_sel:[0,1]
	v_pk_mov_b32 v[122:123], v[2:3], v[2:3] op_sel:[0,1]
	v_pk_mov_b32 v[124:125], v[2:3], v[2:3] op_sel:[0,1]
	v_pk_mov_b32 v[126:127], v[2:3], v[2:3] op_sel:[0,1]
	v_pk_mov_b32 v[128:129], v[2:3], v[2:3] op_sel:[0,1]

.LBB0_1114:
	s_ashr_i32 s17, s16, 31
	s_lshl_b64 s[0:1], s[16:17], 20
	s_add_u32 s18, s42, s0
	s_addc_u32 s19, s43, s1
	s_and_b64 s[0:1], s[6:7], exec
	s_cselect_b32 s17, s19, s5
	s_cselect_b32 s39, s18, s4
	s_ashr_i32 s15, s14, 31
	s_lshl_b64 s[0:1], s[14:15], 20
	s_add_u32 s20, s24, s0
	s_addc_u32 s21, s25, s1
	s_and_b64 s[0:1], s[6:7], exec
	s_cselect_b32 s15, s21, s3
	s_cselect_b32 s40, s20, s2
	s_add_u32 s22, s4, 0x80080
	s_addc_u32 s23, s5, 0
	s_add_u32 s41, s2, 0x100
	v_mov_b32_e32 v2, 0
	s_addc_u32 s49, s3, 0
	s_mov_b32 s58, -2
	v_mov_b32_e32 v3, v2
	v_pk_mov_b32 v[4:5], v[2:3], v[2:3] op_sel:[0,1]
	v_pk_mov_b32 v[6:7], v[2:3], v[2:3] op_sel:[0,1]
	v_pk_mov_b32 v[8:9], v[2:3], v[2:3] op_sel:[0,1]
	v_pk_mov_b32 v[18:19], v[2:3], v[2:3] op_sel:[0,1]
	v_pk_mov_b32 v[20:21], v[2:3], v[2:3] op_sel:[0,1]
	v_pk_mov_b32 v[22:23], v[2:3], v[2:3] op_sel:[0,1]
	v_pk_mov_b32 v[24:25], v[2:3], v[2:3] op_sel:[0,1]
	v_pk_mov_b32 v[34:35], v[2:3], v[2:3] op_sel:[0,1]
	v_pk_mov_b32 v[36:37], v[2:3], v[2:3] op_sel:[0,1]
	v_pk_mov_b32 v[38:39], v[2:3], v[2:3] op_sel:[0,1]
	v_pk_mov_b32 v[40:41], v[2:3], v[2:3] op_sel:[0,1]
	v_pk_mov_b32 v[50:51], v[2:3], v[2:3] op_sel:[0,1]
	v_pk_mov_b32 v[52:53], v[2:3], v[2:3] op_sel:[0,1]
	v_pk_mov_b32 v[54:55], v[2:3], v[2:3] op_sel:[0,1]
	v_pk_mov_b32 v[56:57], v[2:3], v[2:3] op_sel:[0,1]
	v_pk_mov_b32 v[10:11], v[2:3], v[2:3] op_sel:[0,1]
	v_pk_mov_b32 v[12:13], v[2:3], v[2:3] op_sel:[0,1]
	v_pk_mov_b32 v[14:15], v[2:3], v[2:3] op_sel:[0,1]
	v_pk_mov_b32 v[16:17], v[2:3], v[2:3] op_sel:[0,1]
	v_pk_mov_b32 v[26:27], v[2:3], v[2:3] op_sel:[0,1]
	v_pk_mov_b32 v[28:29], v[2:3], v[2:3] op_sel:[0,1]
	v_pk_mov_b32 v[30:31], v[2:3], v[2:3] op_sel:[0,1]
	v_pk_mov_b32 v[32:33], v[2:3], v[2:3] op_sel:[0,1]
	v_pk_mov_b32 v[42:43], v[2:3], v[2:3] op_sel:[0,1]
	v_pk_mov_b32 v[44:45], v[2:3], v[2:3] op_sel:[0,1]
	v_pk_mov_b32 v[46:47], v[2:3], v[2:3] op_sel:[0,1]
	v_pk_mov_b32 v[48:49], v[2:3], v[2:3] op_sel:[0,1]
	v_pk_mov_b32 v[58:59], v[2:3], v[2:3] op_sel:[0,1]
	v_pk_mov_b32 v[60:61], v[2:3], v[2:3] op_sel:[0,1]
	v_pk_mov_b32 v[62:63], v[2:3], v[2:3] op_sel:[0,1]
	v_pk_mov_b32 v[64:65], v[2:3], v[2:3] op_sel:[0,1]
	v_pk_mov_b32 v[66:67], v[2:3], v[2:3] op_sel:[0,1]
	v_pk_mov_b32 v[68:69], v[2:3], v[2:3] op_sel:[0,1]
	v_pk_mov_b32 v[70:71], v[2:3], v[2:3] op_sel:[0,1]
	v_pk_mov_b32 v[72:73], v[2:3], v[2:3] op_sel:[0,1]
	v_pk_mov_b32 v[82:83], v[2:3], v[2:3] op_sel:[0,1]
	v_pk_mov_b32 v[84:85], v[2:3], v[2:3] op_sel:[0,1]
	v_pk_mov_b32 v[86:87], v[2:3], v[2:3] op_sel:[0,1]
	v_pk_mov_b32 v[88:89], v[2:3], v[2:3] op_sel:[0,1]
	v_pk_mov_b32 v[98:99], v[2:3], v[2:3] op_sel:[0,1]
	v_pk_mov_b32 v[100:101], v[2:3], v[2:3] op_sel:[0,1]
	v_pk_mov_b32 v[102:103], v[2:3], v[2:3] op_sel:[0,1]
	v_pk_mov_b32 v[104:105], v[2:3], v[2:3] op_sel:[0,1]
	v_pk_mov_b32 v[114:115], v[2:3], v[2:3] op_sel:[0,1]
	v_pk_mov_b32 v[116:117], v[2:3], v[2:3] op_sel:[0,1]
	v_pk_mov_b32 v[118:119], v[2:3], v[2:3] op_sel:[0,1]
	v_pk_mov_b32 v[120:121], v[2:3], v[2:3] op_sel:[0,1]
	v_pk_mov_b32 v[74:75], v[2:3], v[2:3] op_sel:[0,1]
	v_pk_mov_b32 v[76:77], v[2:3], v[2:3] op_sel:[0,1]
	v_pk_mov_b32 v[78:79], v[2:3], v[2:3] op_sel:[0,1]
	v_pk_mov_b32 v[80:81], v[2:3], v[2:3] op_sel:[0,1]
	v_pk_mov_b32 v[90:91], v[2:3], v[2:3] op_sel:[0,1]
	v_pk_mov_b32 v[92:93], v[2:3], v[2:3] op_sel:[0,1]
	v_pk_mov_b32 v[94:95], v[2:3], v[2:3] op_sel:[0,1]
	v_pk_mov_b32 v[96:97], v[2:3], v[2:3] op_sel:[0,1]
	v_pk_mov_b32 v[106:107], v[2:3], v[2:3] op_sel:[0,1]
	v_pk_mov_b32 v[108:109], v[2:3], v[2:3] op_sel:[0,1]
	v_pk_mov_b32 v[110:111], v[2:3], v[2:3] op_sel:[0,1]
	v_pk_mov_b32 v[112:113], v[2:3], v[2:3] op_sel:[0,1]
	v_pk_mov_b32 v[122:123], v[2:3], v[2:3] op_sel:[0,1]
	v_pk_mov_b32 v[124:125], v[2:3], v[2:3] op_sel:[0,1]
	v_pk_mov_b32 v[126:127], v[2:3], v[2:3] op_sel:[0,1]
	v_pk_mov_b32 v[128:129], v[2:3], v[2:3] op_sel:[0,1]

.LBB0_1241:
	s_add_i32 s93, s93, 1
	s_mul_i32 s0, s93, s96
	s_mov_b32 s2, s95
	s_mov_b32 s67, s95
	s_add_i32 s95, s0, s56
	s_cmpk_lt_i32 s95, 0x200
	s_mov_b32 s3, s66
	s_cselect_b64 s[16:17], -1, 0
	s_ashr_i32 s66, s95, 2
	s_and_b64 s[0:1], s[16:17], exec
	s_cselect_b32 s2, s95, s2
	s_cselect_b32 s0, s66, s3
	s_ashr_i32 s3, s2, 31
	s_lshl_b64 s[2:3], s[2:3], 18
	s_mov_b64 s[18:19], s[14:15]
	s_add_u32 s14, s78, s2
	s_addc_u32 s15, s79, s3
	s_and_b64 s[2:3], s[16:17], exec
	s_cselect_b32 s49, s15, s19
	s_cselect_b32 s58, s14, s18
	s_ashr_i32 s1, s0, 31
	s_lshl_b64 s[0:1], s[0:1], 17
	s_mov_b64 s[20:21], s[6:7]
	s_add_u32 s6, s34, s0
	s_addc_u32 s7, s35, s1
	s_and_b64 s[0:1], s[16:17], exec
	v_mov_b32_e32 v2, 0
	s_mov_b32 s72, s56
	s_cselect_b32 s59, s7, s21
	s_cselect_b32 s60, s6, s20
	s_mov_b64 s[4:5], 0
	s_mov_b64 s[22:23], -1
	s_mov_b64 s[2:3], 0
	v_mov_b32_e32 v3, v2
	v_pk_mov_b32 v[4:5], v[2:3], v[2:3] op_sel:[0,1]
	v_pk_mov_b32 v[6:7], v[2:3], v[2:3] op_sel:[0,1]
	v_pk_mov_b32 v[8:9], v[2:3], v[2:3] op_sel:[0,1]
	v_pk_mov_b32 v[10:11], v[2:3], v[2:3] op_sel:[0,1]
	v_pk_mov_b32 v[12:13], v[2:3], v[2:3] op_sel:[0,1]
	v_pk_mov_b32 v[18:19], v[2:3], v[2:3] op_sel:[0,1]
	v_pk_mov_b32 v[20:21], v[2:3], v[2:3] op_sel:[0,1]
	v_pk_mov_b32 v[26:27], v[2:3], v[2:3] op_sel:[0,1]
	v_pk_mov_b32 v[28:29], v[2:3], v[2:3] op_sel:[0,1]
	v_pk_mov_b32 v[34:35], v[2:3], v[2:3] op_sel:[0,1]
	v_pk_mov_b32 v[36:37], v[2:3], v[2:3] op_sel:[0,1]
	v_pk_mov_b32 v[42:43], v[2:3], v[2:3] op_sel:[0,1]
	v_pk_mov_b32 v[44:45], v[2:3], v[2:3] op_sel:[0,1]
	v_pk_mov_b32 v[50:51], v[2:3], v[2:3] op_sel:[0,1]
	v_pk_mov_b32 v[52:53], v[2:3], v[2:3] op_sel:[0,1]
	v_pk_mov_b32 v[14:15], v[2:3], v[2:3] op_sel:[0,1]
	v_pk_mov_b32 v[16:17], v[2:3], v[2:3] op_sel:[0,1]
	v_pk_mov_b32 v[22:23], v[2:3], v[2:3] op_sel:[0,1]
	v_pk_mov_b32 v[24:25], v[2:3], v[2:3] op_sel:[0,1]
	v_pk_mov_b32 v[30:31], v[2:3], v[2:3] op_sel:[0,1]
	v_pk_mov_b32 v[32:33], v[2:3], v[2:3] op_sel:[0,1]
	v_pk_mov_b32 v[38:39], v[2:3], v[2:3] op_sel:[0,1]
	v_pk_mov_b32 v[40:41], v[2:3], v[2:3] op_sel:[0,1]
	v_pk_mov_b32 v[46:47], v[2:3], v[2:3] op_sel:[0,1]
	v_pk_mov_b32 v[48:49], v[2:3], v[2:3] op_sel:[0,1]
	v_pk_mov_b32 v[54:55], v[2:3], v[2:3] op_sel:[0,1]
	v_pk_mov_b32 v[56:57], v[2:3], v[2:3] op_sel:[0,1]
	v_pk_mov_b32 v[58:59], v[2:3], v[2:3] op_sel:[0,1]
	v_pk_mov_b32 v[60:61], v[2:3], v[2:3] op_sel:[0,1]
	v_pk_mov_b32 v[62:63], v[2:3], v[2:3] op_sel:[0,1]
	v_pk_mov_b32 v[64:65], v[2:3], v[2:3] op_sel:[0,1]
	v_pk_mov_b32 v[66:67], v[2:3], v[2:3] op_sel:[0,1]
	v_pk_mov_b32 v[68:69], v[2:3], v[2:3] op_sel:[0,1]
	v_pk_mov_b32 v[70:71], v[2:3], v[2:3] op_sel:[0,1]
	v_pk_mov_b32 v[72:73], v[2:3], v[2:3] op_sel:[0,1]
	v_pk_mov_b32 v[74:75], v[2:3], v[2:3] op_sel:[0,1]
	v_pk_mov_b32 v[76:77], v[2:3], v[2:3] op_sel:[0,1]
	v_pk_mov_b32 v[82:83], v[2:3], v[2:3] op_sel:[0,1]
	v_pk_mov_b32 v[84:85], v[2:3], v[2:3] op_sel:[0,1]
	v_pk_mov_b32 v[90:91], v[2:3], v[2:3] op_sel:[0,1]
	v_pk_mov_b32 v[92:93], v[2:3], v[2:3] op_sel:[0,1]
	v_pk_mov_b32 v[98:99], v[2:3], v[2:3] op_sel:[0,1]
	v_pk_mov_b32 v[100:101], v[2:3], v[2:3] op_sel:[0,1]
	v_pk_mov_b32 v[106:107], v[2:3], v[2:3] op_sel:[0,1]
	v_pk_mov_b32 v[108:109], v[2:3], v[2:3] op_sel:[0,1]
	v_pk_mov_b32 v[114:115], v[2:3], v[2:3] op_sel:[0,1]
	v_pk_mov_b32 v[116:117], v[2:3], v[2:3] op_sel:[0,1]
	v_pk_mov_b32 v[78:79], v[2:3], v[2:3] op_sel:[0,1]
	v_pk_mov_b32 v[80:81], v[2:3], v[2:3] op_sel:[0,1]
	v_pk_mov_b32 v[86:87], v[2:3], v[2:3] op_sel:[0,1]
	v_pk_mov_b32 v[88:89], v[2:3], v[2:3] op_sel:[0,1]
	v_pk_mov_b32 v[94:95], v[2:3], v[2:3] op_sel:[0,1]
	v_pk_mov_b32 v[96:97], v[2:3], v[2:3] op_sel:[0,1]
	v_pk_mov_b32 v[102:103], v[2:3], v[2:3] op_sel:[0,1]
	v_pk_mov_b32 v[104:105], v[2:3], v[2:3] op_sel:[0,1]
	v_pk_mov_b32 v[110:111], v[2:3], v[2:3] op_sel:[0,1]
	v_pk_mov_b32 v[112:113], v[2:3], v[2:3] op_sel:[0,1]
	v_pk_mov_b32 v[118:119], v[2:3], v[2:3] op_sel:[0,1]
	v_pk_mov_b32 v[120:121], v[2:3], v[2:3] op_sel:[0,1]
	v_pk_mov_b32 v[122:123], v[2:3], v[2:3] op_sel:[0,1]
	v_pk_mov_b32 v[124:125], v[2:3], v[2:3] op_sel:[0,1]
	v_pk_mov_b32 v[126:127], v[2:3], v[2:3] op_sel:[0,1]
	v_pk_mov_b32 v[128:129], v[2:3], v[2:3] op_sel:[0,1]

.LBB0_1362:
	s_add_i32 s31, s31, 1
	s_mul_i32 s4, s31, s96
	s_mov_b64 s[2:3], s[8:9]
	s_mov_b32 s8, s34
	s_mov_b32 s37, s34
	s_add_i32 s34, s4, s56
	s_cmpk_lt_i32 s34, 0x200
	s_mov_b32 s9, s35
	s_mov_b32 s36, s35
	s_cselect_b64 s[18:19], -1, 0
	s_ashr_i32 s35, s34, 2
	s_and_b64 s[4:5], s[18:19], exec
	s_cselect_b32 s8, s34, s8
	s_cselect_b32 s4, s35, s9
	s_ashr_i32 s9, s8, 31
	s_lshl_b64 s[8:9], s[8:9], 18
	s_mov_b64 s[0:1], s[16:17]
	s_add_u32 s16, s78, s8
	s_addc_u32 s17, s79, s9
	s_and_b64 s[8:9], s[18:19], exec
	s_cselect_b32 s38, s17, s1
	s_cselect_b32 s39, s16, s0
	s_ashr_i32 s5, s4, 31
	s_lshl_b64 s[4:5], s[4:5], 18
	s_add_u32 s8, s22, s4
	s_addc_u32 s9, s23, s5
	s_and_b64 s[4:5], s[18:19], exec
	s_cselect_b32 s40, s9, s3
	s_cselect_b32 s41, s8, s2
	s_add_u32 s20, s0, 0x20080
	s_addc_u32 s21, s1, 0
	s_add_u32 s49, s2, 0x100
	v_mov_b32_e32 v2, 0
	s_addc_u32 s58, s3, 0
	s_mov_b32 s59, -2
	v_mov_b32_e32 v3, v2
	v_pk_mov_b32 v[4:5], v[2:3], v[2:3] op_sel:[0,1]
	v_pk_mov_b32 v[6:7], v[2:3], v[2:3] op_sel:[0,1]
	v_pk_mov_b32 v[8:9], v[2:3], v[2:3] op_sel:[0,1]
	v_pk_mov_b32 v[18:19], v[2:3], v[2:3] op_sel:[0,1]
	v_pk_mov_b32 v[20:21], v[2:3], v[2:3] op_sel:[0,1]
	v_pk_mov_b32 v[22:23], v[2:3], v[2:3] op_sel:[0,1]
	v_pk_mov_b32 v[24:25], v[2:3], v[2:3] op_sel:[0,1]
	v_pk_mov_b32 v[34:35], v[2:3], v[2:3] op_sel:[0,1]
	v_pk_mov_b32 v[36:37], v[2:3], v[2:3] op_sel:[0,1]
	v_pk_mov_b32 v[38:39], v[2:3], v[2:3] op_sel:[0,1]
	v_pk_mov_b32 v[40:41], v[2:3], v[2:3] op_sel:[0,1]
	v_pk_mov_b32 v[50:51], v[2:3], v[2:3] op_sel:[0,1]
	v_pk_mov_b32 v[52:53], v[2:3], v[2:3] op_sel:[0,1]
	v_pk_mov_b32 v[54:55], v[2:3], v[2:3] op_sel:[0,1]
	v_pk_mov_b32 v[56:57], v[2:3], v[2:3] op_sel:[0,1]
	v_pk_mov_b32 v[10:11], v[2:3], v[2:3] op_sel:[0,1]
	v_pk_mov_b32 v[12:13], v[2:3], v[2:3] op_sel:[0,1]
	v_pk_mov_b32 v[14:15], v[2:3], v[2:3] op_sel:[0,1]
	v_pk_mov_b32 v[16:17], v[2:3], v[2:3] op_sel:[0,1]
	v_pk_mov_b32 v[26:27], v[2:3], v[2:3] op_sel:[0,1]
	v_pk_mov_b32 v[28:29], v[2:3], v[2:3] op_sel:[0,1]
	v_pk_mov_b32 v[30:31], v[2:3], v[2:3] op_sel:[0,1]
	v_pk_mov_b32 v[32:33], v[2:3], v[2:3] op_sel:[0,1]
	v_pk_mov_b32 v[42:43], v[2:3], v[2:3] op_sel:[0,1]
	v_pk_mov_b32 v[44:45], v[2:3], v[2:3] op_sel:[0,1]
	v_pk_mov_b32 v[46:47], v[2:3], v[2:3] op_sel:[0,1]
	v_pk_mov_b32 v[48:49], v[2:3], v[2:3] op_sel:[0,1]
	v_pk_mov_b32 v[58:59], v[2:3], v[2:3] op_sel:[0,1]
	v_pk_mov_b32 v[60:61], v[2:3], v[2:3] op_sel:[0,1]
	v_pk_mov_b32 v[62:63], v[2:3], v[2:3] op_sel:[0,1]
	v_pk_mov_b32 v[64:65], v[2:3], v[2:3] op_sel:[0,1]
	v_pk_mov_b32 v[66:67], v[2:3], v[2:3] op_sel:[0,1]
	v_pk_mov_b32 v[68:69], v[2:3], v[2:3] op_sel:[0,1]
	v_pk_mov_b32 v[70:71], v[2:3], v[2:3] op_sel:[0,1]
	v_pk_mov_b32 v[72:73], v[2:3], v[2:3] op_sel:[0,1]
	v_pk_mov_b32 v[82:83], v[2:3], v[2:3] op_sel:[0,1]
	v_pk_mov_b32 v[84:85], v[2:3], v[2:3] op_sel:[0,1]
	v_pk_mov_b32 v[86:87], v[2:3], v[2:3] op_sel:[0,1]
	v_pk_mov_b32 v[88:89], v[2:3], v[2:3] op_sel:[0,1]
	v_pk_mov_b32 v[98:99], v[2:3], v[2:3] op_sel:[0,1]
	v_pk_mov_b32 v[100:101], v[2:3], v[2:3] op_sel:[0,1]
	v_pk_mov_b32 v[102:103], v[2:3], v[2:3] op_sel:[0,1]
	v_pk_mov_b32 v[104:105], v[2:3], v[2:3] op_sel:[0,1]
	v_pk_mov_b32 v[114:115], v[2:3], v[2:3] op_sel:[0,1]
	v_pk_mov_b32 v[116:117], v[2:3], v[2:3] op_sel:[0,1]
	v_pk_mov_b32 v[118:119], v[2:3], v[2:3] op_sel:[0,1]
	v_pk_mov_b32 v[120:121], v[2:3], v[2:3] op_sel:[0,1]
	v_pk_mov_b32 v[74:75], v[2:3], v[2:3] op_sel:[0,1]
	v_pk_mov_b32 v[76:77], v[2:3], v[2:3] op_sel:[0,1]
	v_pk_mov_b32 v[78:79], v[2:3], v[2:3] op_sel:[0,1]
	v_pk_mov_b32 v[80:81], v[2:3], v[2:3] op_sel:[0,1]
	v_pk_mov_b32 v[90:91], v[2:3], v[2:3] op_sel:[0,1]
	v_pk_mov_b32 v[92:93], v[2:3], v[2:3] op_sel:[0,1]
	v_pk_mov_b32 v[94:95], v[2:3], v[2:3] op_sel:[0,1]
	v_pk_mov_b32 v[96:97], v[2:3], v[2:3] op_sel:[0,1]
	v_pk_mov_b32 v[106:107], v[2:3], v[2:3] op_sel:[0,1]
	v_pk_mov_b32 v[108:109], v[2:3], v[2:3] op_sel:[0,1]
	v_pk_mov_b32 v[110:111], v[2:3], v[2:3] op_sel:[0,1]
	v_pk_mov_b32 v[112:113], v[2:3], v[2:3] op_sel:[0,1]
	v_pk_mov_b32 v[122:123], v[2:3], v[2:3] op_sel:[0,1]
	v_pk_mov_b32 v[124:125], v[2:3], v[2:3] op_sel:[0,1]
	v_pk_mov_b32 v[126:127], v[2:3], v[2:3] op_sel:[0,1]
	v_pk_mov_b32 v[128:129], v[2:3], v[2:3] op_sel:[0,1]

.LBB0_1427:
	s_ashr_i32 s17, s16, 31
	s_lshl_b64 s[0:1], s[16:17], 20
	s_add_u32 s18, s64, s0
	s_addc_u32 s19, s65, s1
	s_and_b64 s[0:1], s[6:7], exec
	s_cselect_b32 s17, s19, s5
	s_cselect_b32 s49, s18, s4
	s_ashr_i32 s15, s14, 31
	s_lshl_b64 s[0:1], s[14:15], 20
	s_add_u32 s20, s28, s0
	s_addc_u32 s21, s29, s1
	s_and_b64 s[0:1], s[6:7], exec
	s_cselect_b32 s15, s21, s3
	s_cselect_b32 s58, s20, s2
	s_add_u32 s26, s4, 0x80080
	s_addc_u32 s27, s5, 0
	s_add_u32 s59, s2, 0x100
	v_mov_b32_e32 v2, 0
	s_addc_u32 s60, s3, 0
	s_mov_b32 s61, -2
	v_mov_b32_e32 v3, v2
	v_pk_mov_b32 v[4:5], v[2:3], v[2:3] op_sel:[0,1]
	v_pk_mov_b32 v[10:11], v[2:3], v[2:3] op_sel:[0,1]
	v_pk_mov_b32 v[12:13], v[2:3], v[2:3] op_sel:[0,1]
	v_pk_mov_b32 v[18:19], v[2:3], v[2:3] op_sel:[0,1]
	v_pk_mov_b32 v[20:21], v[2:3], v[2:3] op_sel:[0,1]
	v_pk_mov_b32 v[26:27], v[2:3], v[2:3] op_sel:[0,1]
	v_pk_mov_b32 v[28:29], v[2:3], v[2:3] op_sel:[0,1]
	v_pk_mov_b32 v[34:35], v[2:3], v[2:3] op_sel:[0,1]
	v_pk_mov_b32 v[36:37], v[2:3], v[2:3] op_sel:[0,1]
	v_pk_mov_b32 v[42:43], v[2:3], v[2:3] op_sel:[0,1]
	v_pk_mov_b32 v[44:45], v[2:3], v[2:3] op_sel:[0,1]
	v_pk_mov_b32 v[50:51], v[2:3], v[2:3] op_sel:[0,1]
	v_pk_mov_b32 v[52:53], v[2:3], v[2:3] op_sel:[0,1]
	v_pk_mov_b32 v[58:59], v[2:3], v[2:3] op_sel:[0,1]
	v_pk_mov_b32 v[60:61], v[2:3], v[2:3] op_sel:[0,1]
	v_pk_mov_b32 v[6:7], v[2:3], v[2:3] op_sel:[0,1]
	v_pk_mov_b32 v[8:9], v[2:3], v[2:3] op_sel:[0,1]
	v_pk_mov_b32 v[14:15], v[2:3], v[2:3] op_sel:[0,1]
	v_pk_mov_b32 v[16:17], v[2:3], v[2:3] op_sel:[0,1]
	v_pk_mov_b32 v[22:23], v[2:3], v[2:3] op_sel:[0,1]
	v_pk_mov_b32 v[24:25], v[2:3], v[2:3] op_sel:[0,1]
	v_pk_mov_b32 v[30:31], v[2:3], v[2:3] op_sel:[0,1]
	v_pk_mov_b32 v[32:33], v[2:3], v[2:3] op_sel:[0,1]
	v_pk_mov_b32 v[38:39], v[2:3], v[2:3] op_sel:[0,1]
	v_pk_mov_b32 v[40:41], v[2:3], v[2:3] op_sel:[0,1]
	v_pk_mov_b32 v[46:47], v[2:3], v[2:3] op_sel:[0,1]
	v_pk_mov_b32 v[48:49], v[2:3], v[2:3] op_sel:[0,1]
	v_pk_mov_b32 v[54:55], v[2:3], v[2:3] op_sel:[0,1]
	v_pk_mov_b32 v[56:57], v[2:3], v[2:3] op_sel:[0,1]
	v_pk_mov_b32 v[62:63], v[2:3], v[2:3] op_sel:[0,1]
	v_pk_mov_b32 v[64:65], v[2:3], v[2:3] op_sel:[0,1]
	v_pk_mov_b32 v[66:67], v[2:3], v[2:3] op_sel:[0,1]
	v_pk_mov_b32 v[68:69], v[2:3], v[2:3] op_sel:[0,1]
	v_pk_mov_b32 v[74:75], v[2:3], v[2:3] op_sel:[0,1]
	v_pk_mov_b32 v[76:77], v[2:3], v[2:3] op_sel:[0,1]
	v_pk_mov_b32 v[82:83], v[2:3], v[2:3] op_sel:[0,1]
	v_pk_mov_b32 v[84:85], v[2:3], v[2:3] op_sel:[0,1]
	v_pk_mov_b32 v[90:91], v[2:3], v[2:3] op_sel:[0,1]
	v_pk_mov_b32 v[92:93], v[2:3], v[2:3] op_sel:[0,1]
	v_pk_mov_b32 v[98:99], v[2:3], v[2:3] op_sel:[0,1]
	v_pk_mov_b32 v[100:101], v[2:3], v[2:3] op_sel:[0,1]
	v_pk_mov_b32 v[106:107], v[2:3], v[2:3] op_sel:[0,1]
	v_pk_mov_b32 v[108:109], v[2:3], v[2:3] op_sel:[0,1]
	v_pk_mov_b32 v[114:115], v[2:3], v[2:3] op_sel:[0,1]
	v_pk_mov_b32 v[116:117], v[2:3], v[2:3] op_sel:[0,1]
	v_pk_mov_b32 v[122:123], v[2:3], v[2:3] op_sel:[0,1]
	v_pk_mov_b32 v[124:125], v[2:3], v[2:3] op_sel:[0,1]
	v_pk_mov_b32 v[70:71], v[2:3], v[2:3] op_sel:[0,1]
	v_pk_mov_b32 v[72:73], v[2:3], v[2:3] op_sel:[0,1]
	v_pk_mov_b32 v[78:79], v[2:3], v[2:3] op_sel:[0,1]
	v_pk_mov_b32 v[80:81], v[2:3], v[2:3] op_sel:[0,1]
	v_pk_mov_b32 v[86:87], v[2:3], v[2:3] op_sel:[0,1]
	v_pk_mov_b32 v[88:89], v[2:3], v[2:3] op_sel:[0,1]
	v_pk_mov_b32 v[94:95], v[2:3], v[2:3] op_sel:[0,1]
	v_pk_mov_b32 v[96:97], v[2:3], v[2:3] op_sel:[0,1]
	v_pk_mov_b32 v[102:103], v[2:3], v[2:3] op_sel:[0,1]
	v_pk_mov_b32 v[104:105], v[2:3], v[2:3] op_sel:[0,1]
	v_pk_mov_b32 v[110:111], v[2:3], v[2:3] op_sel:[0,1]
	v_pk_mov_b32 v[112:113], v[2:3], v[2:3] op_sel:[0,1]
	v_pk_mov_b32 v[118:119], v[2:3], v[2:3] op_sel:[0,1]
	v_pk_mov_b32 v[120:121], v[2:3], v[2:3] op_sel:[0,1]
	v_pk_mov_b32 v[130:131], v[2:3], v[2:3] op_sel:[0,1]
	v_pk_mov_b32 v[132:133], v[2:3], v[2:3] op_sel:[0,1]

.LBB0_1593:
	s_ashr_i32 s19, s18, 31
	s_lshl_b64 s[0:1], s[18:19], 20
	s_add_u32 s20, s42, s0
	s_addc_u32 s21, s43, s1
	s_and_b64 s[0:1], s[8:9], exec
	s_cselect_b32 s19, s21, s5
	s_cselect_b32 s49, s20, s4
	s_ashr_i32 s17, s16, 31
	s_lshl_b64 s[0:1], s[16:17], 20
	s_add_u32 s22, s30, s0
	s_addc_u32 s23, s31, s1
	s_and_b64 s[0:1], s[8:9], exec
	s_cselect_b32 s17, s23, s3
	s_cselect_b32 s58, s22, s2
	s_add_u32 s28, s4, 0x80080
	s_addc_u32 s29, s5, 0
	s_add_u32 s59, s2, 0x100
	v_mov_b32_e32 v2, 0
	s_addc_u32 s60, s3, 0
	s_mov_b32 s61, -2
	v_mov_b32_e32 v3, v2
	v_pk_mov_b32 v[4:5], v[2:3], v[2:3] op_sel:[0,1]
	v_pk_mov_b32 v[10:11], v[2:3], v[2:3] op_sel:[0,1]
	v_pk_mov_b32 v[12:13], v[2:3], v[2:3] op_sel:[0,1]
	v_pk_mov_b32 v[18:19], v[2:3], v[2:3] op_sel:[0,1]
	v_pk_mov_b32 v[20:21], v[2:3], v[2:3] op_sel:[0,1]
	v_pk_mov_b32 v[26:27], v[2:3], v[2:3] op_sel:[0,1]
	v_pk_mov_b32 v[28:29], v[2:3], v[2:3] op_sel:[0,1]
	v_pk_mov_b32 v[34:35], v[2:3], v[2:3] op_sel:[0,1]
	v_pk_mov_b32 v[36:37], v[2:3], v[2:3] op_sel:[0,1]
	v_pk_mov_b32 v[42:43], v[2:3], v[2:3] op_sel:[0,1]
	v_pk_mov_b32 v[44:45], v[2:3], v[2:3] op_sel:[0,1]
	v_pk_mov_b32 v[50:51], v[2:3], v[2:3] op_sel:[0,1]
	v_pk_mov_b32 v[52:53], v[2:3], v[2:3] op_sel:[0,1]
	v_pk_mov_b32 v[58:59], v[2:3], v[2:3] op_sel:[0,1]
	v_pk_mov_b32 v[60:61], v[2:3], v[2:3] op_sel:[0,1]
	v_pk_mov_b32 v[6:7], v[2:3], v[2:3] op_sel:[0,1]
	v_pk_mov_b32 v[8:9], v[2:3], v[2:3] op_sel:[0,1]
	v_pk_mov_b32 v[14:15], v[2:3], v[2:3] op_sel:[0,1]
	v_pk_mov_b32 v[16:17], v[2:3], v[2:3] op_sel:[0,1]
	v_pk_mov_b32 v[22:23], v[2:3], v[2:3] op_sel:[0,1]
	v_pk_mov_b32 v[24:25], v[2:3], v[2:3] op_sel:[0,1]
	v_pk_mov_b32 v[30:31], v[2:3], v[2:3] op_sel:[0,1]
	v_pk_mov_b32 v[32:33], v[2:3], v[2:3] op_sel:[0,1]
	v_pk_mov_b32 v[38:39], v[2:3], v[2:3] op_sel:[0,1]
	v_pk_mov_b32 v[40:41], v[2:3], v[2:3] op_sel:[0,1]
	v_pk_mov_b32 v[46:47], v[2:3], v[2:3] op_sel:[0,1]
	v_pk_mov_b32 v[48:49], v[2:3], v[2:3] op_sel:[0,1]
	v_pk_mov_b32 v[54:55], v[2:3], v[2:3] op_sel:[0,1]
	v_pk_mov_b32 v[56:57], v[2:3], v[2:3] op_sel:[0,1]
	v_pk_mov_b32 v[62:63], v[2:3], v[2:3] op_sel:[0,1]
	v_pk_mov_b32 v[64:65], v[2:3], v[2:3] op_sel:[0,1]
	v_pk_mov_b32 v[66:67], v[2:3], v[2:3] op_sel:[0,1]
	v_pk_mov_b32 v[68:69], v[2:3], v[2:3] op_sel:[0,1]
	v_pk_mov_b32 v[74:75], v[2:3], v[2:3] op_sel:[0,1]
	v_pk_mov_b32 v[76:77], v[2:3], v[2:3] op_sel:[0,1]
	v_pk_mov_b32 v[82:83], v[2:3], v[2:3] op_sel:[0,1]
	v_pk_mov_b32 v[84:85], v[2:3], v[2:3] op_sel:[0,1]
	v_pk_mov_b32 v[90:91], v[2:3], v[2:3] op_sel:[0,1]
	v_pk_mov_b32 v[92:93], v[2:3], v[2:3] op_sel:[0,1]
	v_pk_mov_b32 v[98:99], v[2:3], v[2:3] op_sel:[0,1]
	v_pk_mov_b32 v[100:101], v[2:3], v[2:3] op_sel:[0,1]
	v_pk_mov_b32 v[106:107], v[2:3], v[2:3] op_sel:[0,1]
	v_pk_mov_b32 v[108:109], v[2:3], v[2:3] op_sel:[0,1]
	v_pk_mov_b32 v[114:115], v[2:3], v[2:3] op_sel:[0,1]
	v_pk_mov_b32 v[116:117], v[2:3], v[2:3] op_sel:[0,1]
	v_pk_mov_b32 v[122:123], v[2:3], v[2:3] op_sel:[0,1]
	v_pk_mov_b32 v[124:125], v[2:3], v[2:3] op_sel:[0,1]
	v_pk_mov_b32 v[70:71], v[2:3], v[2:3] op_sel:[0,1]
	v_pk_mov_b32 v[72:73], v[2:3], v[2:3] op_sel:[0,1]
	v_pk_mov_b32 v[78:79], v[2:3], v[2:3] op_sel:[0,1]
	v_pk_mov_b32 v[80:81], v[2:3], v[2:3] op_sel:[0,1]
	v_pk_mov_b32 v[86:87], v[2:3], v[2:3] op_sel:[0,1]
	v_pk_mov_b32 v[88:89], v[2:3], v[2:3] op_sel:[0,1]
	v_pk_mov_b32 v[94:95], v[2:3], v[2:3] op_sel:[0,1]
	v_pk_mov_b32 v[96:97], v[2:3], v[2:3] op_sel:[0,1]
	v_pk_mov_b32 v[102:103], v[2:3], v[2:3] op_sel:[0,1]
	v_pk_mov_b32 v[104:105], v[2:3], v[2:3] op_sel:[0,1]
	v_pk_mov_b32 v[110:111], v[2:3], v[2:3] op_sel:[0,1]
	v_pk_mov_b32 v[112:113], v[2:3], v[2:3] op_sel:[0,1]
	v_pk_mov_b32 v[118:119], v[2:3], v[2:3] op_sel:[0,1]
	v_pk_mov_b32 v[120:121], v[2:3], v[2:3] op_sel:[0,1]
	v_pk_mov_b32 v[126:127], v[2:3], v[2:3] op_sel:[0,1]
	v_pk_mov_b32 v[128:129], v[2:3], v[2:3] op_sel:[0,1]

.LBB0_1717:
	s_add_u32 s49, s18, 0x100
	v_mov_b32_e32 v2, 0
	s_addc_u32 s58, s19, 0
	s_mov_b32 s59, -2
	v_mov_b32_e32 v3, v2
	v_pk_mov_b32 v[4:5], v[2:3], v[2:3] op_sel:[0,1]
	v_pk_mov_b32 v[6:7], v[2:3], v[2:3] op_sel:[0,1]
	v_pk_mov_b32 v[8:9], v[2:3], v[2:3] op_sel:[0,1]
	v_pk_mov_b32 v[18:19], v[2:3], v[2:3] op_sel:[0,1]
	v_pk_mov_b32 v[20:21], v[2:3], v[2:3] op_sel:[0,1]
	v_pk_mov_b32 v[22:23], v[2:3], v[2:3] op_sel:[0,1]
	v_pk_mov_b32 v[24:25], v[2:3], v[2:3] op_sel:[0,1]
	v_pk_mov_b32 v[34:35], v[2:3], v[2:3] op_sel:[0,1]
	v_pk_mov_b32 v[36:37], v[2:3], v[2:3] op_sel:[0,1]
	v_pk_mov_b32 v[38:39], v[2:3], v[2:3] op_sel:[0,1]
	v_pk_mov_b32 v[40:41], v[2:3], v[2:3] op_sel:[0,1]
	v_pk_mov_b32 v[50:51], v[2:3], v[2:3] op_sel:[0,1]
	v_pk_mov_b32 v[52:53], v[2:3], v[2:3] op_sel:[0,1]
	v_pk_mov_b32 v[54:55], v[2:3], v[2:3] op_sel:[0,1]
	v_pk_mov_b32 v[56:57], v[2:3], v[2:3] op_sel:[0,1]
	v_pk_mov_b32 v[10:11], v[2:3], v[2:3] op_sel:[0,1]
	v_pk_mov_b32 v[12:13], v[2:3], v[2:3] op_sel:[0,1]
	v_pk_mov_b32 v[14:15], v[2:3], v[2:3] op_sel:[0,1]
	v_pk_mov_b32 v[16:17], v[2:3], v[2:3] op_sel:[0,1]
	v_pk_mov_b32 v[26:27], v[2:3], v[2:3] op_sel:[0,1]
	v_pk_mov_b32 v[28:29], v[2:3], v[2:3] op_sel:[0,1]
	v_pk_mov_b32 v[30:31], v[2:3], v[2:3] op_sel:[0,1]
	v_pk_mov_b32 v[32:33], v[2:3], v[2:3] op_sel:[0,1]
	v_pk_mov_b32 v[42:43], v[2:3], v[2:3] op_sel:[0,1]
	v_pk_mov_b32 v[44:45], v[2:3], v[2:3] op_sel:[0,1]
	v_pk_mov_b32 v[46:47], v[2:3], v[2:3] op_sel:[0,1]
	v_pk_mov_b32 v[48:49], v[2:3], v[2:3] op_sel:[0,1]
	v_pk_mov_b32 v[58:59], v[2:3], v[2:3] op_sel:[0,1]
	v_pk_mov_b32 v[60:61], v[2:3], v[2:3] op_sel:[0,1]
	v_pk_mov_b32 v[62:63], v[2:3], v[2:3] op_sel:[0,1]
	v_pk_mov_b32 v[64:65], v[2:3], v[2:3] op_sel:[0,1]
	v_pk_mov_b32 v[66:67], v[2:3], v[2:3] op_sel:[0,1]
	v_pk_mov_b32 v[68:69], v[2:3], v[2:3] op_sel:[0,1]
	v_pk_mov_b32 v[70:71], v[2:3], v[2:3] op_sel:[0,1]
	v_pk_mov_b32 v[72:73], v[2:3], v[2:3] op_sel:[0,1]
	v_pk_mov_b32 v[90:91], v[2:3], v[2:3] op_sel:[0,1]
	v_pk_mov_b32 v[92:93], v[2:3], v[2:3] op_sel:[0,1]
	v_pk_mov_b32 v[102:103], v[2:3], v[2:3] op_sel:[0,1]
	v_pk_mov_b32 v[104:105], v[2:3], v[2:3] op_sel:[0,1]
	v_pk_mov_b32 v[122:123], v[2:3], v[2:3] op_sel:[0,1]
	v_pk_mov_b32 v[124:125], v[2:3], v[2:3] op_sel:[0,1]
	v_pk_mov_b32 v[130:131], v[2:3], v[2:3] op_sel:[0,1]
	v_pk_mov_b32 v[132:133], v[2:3], v[2:3] op_sel:[0,1]
	v_pk_mov_b32 v[150:151], v[2:3], v[2:3] op_sel:[0,1]
	v_pk_mov_b32 v[152:153], v[2:3], v[2:3] op_sel:[0,1]
	v_pk_mov_b32 v[154:155], v[2:3], v[2:3] op_sel:[0,1]
	v_pk_mov_b32 v[156:157], v[2:3], v[2:3] op_sel:[0,1]
	v_pk_mov_b32 v[74:75], v[2:3], v[2:3] op_sel:[0,1]
	v_pk_mov_b32 v[76:77], v[2:3], v[2:3] op_sel:[0,1]
	v_pk_mov_b32 v[86:87], v[2:3], v[2:3] op_sel:[0,1]
	v_pk_mov_b32 v[88:89], v[2:3], v[2:3] op_sel:[0,1]
	v_pk_mov_b32 v[114:115], v[2:3], v[2:3] op_sel:[0,1]
	v_pk_mov_b32 v[116:117], v[2:3], v[2:3] op_sel:[0,1]
	v_pk_mov_b32 v[118:119], v[2:3], v[2:3] op_sel:[0,1]
	v_pk_mov_b32 v[120:121], v[2:3], v[2:3] op_sel:[0,1]
	v_pk_mov_b32 v[138:139], v[2:3], v[2:3] op_sel:[0,1]
	v_pk_mov_b32 v[140:141], v[2:3], v[2:3] op_sel:[0,1]
	v_pk_mov_b32 v[142:143], v[2:3], v[2:3] op_sel:[0,1]
	v_pk_mov_b32 v[144:145], v[2:3], v[2:3] op_sel:[0,1]
	v_pk_mov_b32 v[162:163], v[2:3], v[2:3] op_sel:[0,1]
	v_pk_mov_b32 v[164:165], v[2:3], v[2:3] op_sel:[0,1]
	v_pk_mov_b32 v[170:171], v[2:3], v[2:3] op_sel:[0,1]
	v_pk_mov_b32 v[172:173], v[2:3], v[2:3] op_sel:[0,1]

.LBB0_1738:
	s_add_u32 s40, s16, 0x100
	v_mov_b32_e32 v2, 0
	s_addc_u32 s41, s17, 0
	s_mov_b32 s49, -2
	v_mov_b32_e32 v3, v2
	v_pk_mov_b32 v[4:5], v[2:3], v[2:3] op_sel:[0,1]
	v_pk_mov_b32 v[6:7], v[2:3], v[2:3] op_sel:[0,1]
	v_pk_mov_b32 v[8:9], v[2:3], v[2:3] op_sel:[0,1]
	v_pk_mov_b32 v[10:11], v[2:3], v[2:3] op_sel:[0,1]
	v_pk_mov_b32 v[12:13], v[2:3], v[2:3] op_sel:[0,1]
	v_pk_mov_b32 v[14:15], v[2:3], v[2:3] op_sel:[0,1]
	v_pk_mov_b32 v[16:17], v[2:3], v[2:3] op_sel:[0,1]
	v_pk_mov_b32 v[26:27], v[2:3], v[2:3] op_sel:[0,1]
	v_pk_mov_b32 v[28:29], v[2:3], v[2:3] op_sel:[0,1]
	v_pk_mov_b32 v[30:31], v[2:3], v[2:3] op_sel:[0,1]
	v_pk_mov_b32 v[32:33], v[2:3], v[2:3] op_sel:[0,1]
	v_pk_mov_b32 v[42:43], v[2:3], v[2:3] op_sel:[0,1]
	v_pk_mov_b32 v[44:45], v[2:3], v[2:3] op_sel:[0,1]
	v_pk_mov_b32 v[46:47], v[2:3], v[2:3] op_sel:[0,1]
	v_pk_mov_b32 v[48:49], v[2:3], v[2:3] op_sel:[0,1]
	v_pk_mov_b32 v[18:19], v[2:3], v[2:3] op_sel:[0,1]
	v_pk_mov_b32 v[20:21], v[2:3], v[2:3] op_sel:[0,1]
	v_pk_mov_b32 v[22:23], v[2:3], v[2:3] op_sel:[0,1]
	v_pk_mov_b32 v[24:25], v[2:3], v[2:3] op_sel:[0,1]
	v_pk_mov_b32 v[34:35], v[2:3], v[2:3] op_sel:[0,1]
	v_pk_mov_b32 v[36:37], v[2:3], v[2:3] op_sel:[0,1]
	v_pk_mov_b32 v[38:39], v[2:3], v[2:3] op_sel:[0,1]
	v_pk_mov_b32 v[40:41], v[2:3], v[2:3] op_sel:[0,1]
	v_pk_mov_b32 v[50:51], v[2:3], v[2:3] op_sel:[0,1]
	v_pk_mov_b32 v[52:53], v[2:3], v[2:3] op_sel:[0,1]
	v_pk_mov_b32 v[54:55], v[2:3], v[2:3] op_sel:[0,1]
	v_pk_mov_b32 v[56:57], v[2:3], v[2:3] op_sel:[0,1]
	v_pk_mov_b32 v[58:59], v[2:3], v[2:3] op_sel:[0,1]
	v_pk_mov_b32 v[60:61], v[2:3], v[2:3] op_sel:[0,1]
	v_pk_mov_b32 v[62:63], v[2:3], v[2:3] op_sel:[0,1]
	v_pk_mov_b32 v[64:65], v[2:3], v[2:3] op_sel:[0,1]
	v_pk_mov_b32 v[66:67], v[2:3], v[2:3] op_sel:[0,1]
	v_pk_mov_b32 v[68:69], v[2:3], v[2:3] op_sel:[0,1]
	v_pk_mov_b32 v[70:71], v[2:3], v[2:3] op_sel:[0,1]
	v_pk_mov_b32 v[72:73], v[2:3], v[2:3] op_sel:[0,1]
	v_pk_mov_b32 v[74:75], v[2:3], v[2:3] op_sel:[0,1]
	v_pk_mov_b32 v[76:77], v[2:3], v[2:3] op_sel:[0,1]
	v_pk_mov_b32 v[78:79], v[2:3], v[2:3] op_sel:[0,1]
	v_pk_mov_b32 v[80:81], v[2:3], v[2:3] op_sel:[0,1]
	v_pk_mov_b32 v[86:87], v[2:3], v[2:3] op_sel:[0,1]
	v_pk_mov_b32 v[88:89], v[2:3], v[2:3] op_sel:[0,1]
	v_pk_mov_b32 v[94:95], v[2:3], v[2:3] op_sel:[0,1]
	v_pk_mov_b32 v[96:97], v[2:3], v[2:3] op_sel:[0,1]
	v_pk_mov_b32 v[102:103], v[2:3], v[2:3] op_sel:[0,1]
	v_pk_mov_b32 v[104:105], v[2:3], v[2:3] op_sel:[0,1]
	v_pk_mov_b32 v[110:111], v[2:3], v[2:3] op_sel:[0,1]
	v_pk_mov_b32 v[112:113], v[2:3], v[2:3] op_sel:[0,1]
	v_pk_mov_b32 v[82:83], v[2:3], v[2:3] op_sel:[0,1]
	v_pk_mov_b32 v[84:85], v[2:3], v[2:3] op_sel:[0,1]
	v_pk_mov_b32 v[90:91], v[2:3], v[2:3] op_sel:[0,1]
	v_pk_mov_b32 v[92:93], v[2:3], v[2:3] op_sel:[0,1]
	v_pk_mov_b32 v[98:99], v[2:3], v[2:3] op_sel:[0,1]
	v_pk_mov_b32 v[100:101], v[2:3], v[2:3] op_sel:[0,1]
	v_pk_mov_b32 v[106:107], v[2:3], v[2:3] op_sel:[0,1]
	v_pk_mov_b32 v[108:109], v[2:3], v[2:3] op_sel:[0,1]
	v_pk_mov_b32 v[114:115], v[2:3], v[2:3] op_sel:[0,1]
	v_pk_mov_b32 v[116:117], v[2:3], v[2:3] op_sel:[0,1]
	v_pk_mov_b32 v[118:119], v[2:3], v[2:3] op_sel:[0,1]
	v_pk_mov_b32 v[120:121], v[2:3], v[2:3] op_sel:[0,1]
	v_pk_mov_b32 v[122:123], v[2:3], v[2:3] op_sel:[0,1]
	v_pk_mov_b32 v[124:125], v[2:3], v[2:3] op_sel:[0,1]
	v_pk_mov_b32 v[126:127], v[2:3], v[2:3] op_sel:[0,1]
	v_pk_mov_b32 v[128:129], v[2:3], v[2:3] op_sel:[0,1]
